# v47 without the P5-wait SSE touch (touch pruning)
# baseline (speedup 1.0000x reference)
.LBB0_653:
	s_add_u32 s26, s6, 0x8000
	v_readlane_b32 s36, v251, 6
	s_addc_u32 s27, s7, 0
	v_readlane_b32 s50, v251, 20
	v_readlane_b32 s51, v251, 21
	s_add_u32 s16, s50, 0x28200
	s_addc_u32 s17, s51, 0
	s_add_u32 s24, s50, 0x2300000
	s_addc_u32 s25, s51, 0
	s_add_u32 s14, s50, 0x3000000
	s_addc_u32 s15, s51, 0
	s_add_u32 s12, s50, 0x3300000
	s_addc_u32 s13, s51, 0
	s_add_u32 s18, s50, 0xf800000
	s_addc_u32 s19, s51, 0
	s_add_u32 s10, s50, 0x3500000
	s_addc_u32 s11, s51, 0
	s_cmp_lt_i32 s72, 6
	s_cselect_b64 s[2:3], -1, 0
	s_cmp_gt_i32 s73, 5
	s_cselect_b64 s[4:5], -1, 0
	s_and_b64 s[2:3], s[2:3], s[4:5]
	s_andn2_b64 vcc, exec, s[2:3]
	v_readlane_b32 s37, v251, 7
	v_readlane_b32 s38, v251, 8
	v_readlane_b32 s39, v251, 9
	v_readlane_b32 s40, v251, 10
	v_readlane_b32 s41, v251, 11
	v_readlane_b32 s42, v251, 12
	v_readlane_b32 s43, v251, 13
	v_readlane_b32 s44, v251, 14
	v_readlane_b32 s45, v251, 15
	v_readlane_b32 s46, v251, 16
	v_readlane_b32 s47, v251, 17
	v_readlane_b32 s48, v251, 18
	v_readlane_b32 s49, v251, 19
	s_cbranch_vccnz .LBB0_732
	v_readfirstlane_b32 s98, v0
	s_cmp_lt_u32 s98, 64
	s_cbranch_scc1 .Lmy_t5_skip
	v_readlane_b32 s98, v251, 20
	v_readlane_b32 s99, v251, 21
	s_lshl_b32 s100, s70, 15
	s_add_u32 s100, s100, 0x1200000
	s_add_u32 s98, s98, s100
	s_addc_u32 s99, s99, 0
	v_add_u32_e32 v252, 0xffffffc0, v0
	v_lshlrev_b32_e32 v252, 6, v252
	s_nop 1
	global_load_dword v255, v252, s[98:99]
	v_add_u32_e32 v253, 0x7000, v252
	global_load_dword v255, v253, s[98:99]
.Lmy_t5_skip:
	v_cmp_gt_u32_e64 s[2:3], 64, v0
	s_and_saveexec_b64 s[4:5], s[2:3]
	s_cbranch_execz .LBB0_666
	v_readfirstlane_b32 s98, v254
	s_cmpk_gt_u32 s98, 2
	s_cbranch_scc1 .LBB0_665
	v_readfirstlane_b32 s98, v255
	s_cmpk_gt_u32 s98, 3
	s_cbranch_scc1 .LBB0_665
	s_memrealtime s[6:7]
	v_mov_b32_e32 v4, 0
	v_mov_b64_e32 v[2:3], 0x1e8481
	s_branch .LBB0_658
